# v85 + sc1 (write-through) on the 16-byte RAW epilogue stores of the out-proj and down-proj GEMM phases, to leave fewer dirty L2 lines for the grid barrier's write-back
# speedup vs baseline: 1.0077x; 1.0077x over previous
; __device__ __forceinline__ unsigned cvt_pk_bf16(float lo, float hi) { unsigned r; asm volatile("v_cvt_pk_bf16_f32 %0, %1, %2" : "=v"(r) : "v"(lo), "v"(hi)); return r; }
;     __device__ __forceinline__ void operator()(const f32x4 (&acc)[2][2][4][2], const Unit& u, int wr, int wc, int fr, int fq) const {
;         const int row0 = u.pm * BM + wr * 64 + fr, col0 = u.pn * BM + wc * 32 + 8 * fq;
; #pragma unroll
;         for (int ai = 0; ai < 2; ++ai)
; #pragma unroll
;             for (int m = 0; m < 4; ++m) { const int r = row0 + ai * HALF + m * 16; bf16_t* rowp = C + (size_t)r * ldc + col0; float s = 0.f;
; #pragma unroll
;                 for (int bj = 0; bj < 2; ++bj) { const f32x4 v0 = acc[ai][bj][m][0], v1 = acc[ai][bj][m][1];
;                     s += (v0[0] * v0[0] + v0[1] * v0[1]) + (v0[2] * v0[2] + v0[3] * v0[3]) + (v1[0] * v1[0] + v1[1] * v1[1]) + (v1[2] * v1[2] + v1[3] * v1[3]);
;                     u32x4 w; w.x = cvt_pk_bf16(v0[0], v0[1]); w.y = cvt_pk_bf16(v0[2], v0[3]); w.z = cvt_pk_bf16(v1[0], v1[1]); w.w = cvt_pk_bf16(v1[2], v1[3]);
;                     *(u32x4*)(rowp + bj * HALF) = w; }
;                 s += __shfl_xor(s, 16); s += __shfl_xor(s, 32);
;                 if (fq == 0) ssq[(size_t)r * 32 + u.pn * 4 + wc] = s; }
.LBB0_1198:
	v_lshl_add_u32 v146, s28, 8, v148
	v_ashrrev_i32_e32 v147, 31, v146
	v_lshl_or_b32 v144, s8, 8, v150
	v_lshlrev_b64 v[156:157], 12, v[146:147]
	v_ashrrev_i32_e32 v145, 31, v144
	v_lshl_add_u64 v[156:157], s[12:13], 0, v[156:157]
	v_lshl_add_u64 v[160:161], v[144:145], 1, v[156:157]
	v_mul_f32_e32 v155, v125, v125
	v_mul_f32_e32 v156, v127, v127
	v_fmac_f32_e32 v155, v124, v124
	v_fmac_f32_e32 v156, v126, v126
	v_add_f32_e32 v155, v155, v156
	v_mul_f32_e32 v156, v121, v121
	v_fmac_f32_e32 v156, v120, v120
	v_add_f32_e32 v155, v155, v156
	v_mul_f32_e32 v156, v123, v123
	v_fmac_f32_e32 v156, v122, v122
	v_add_f32_e32 v155, v156, v155
	v_cvt_pk_bf16_f32 v156, v124, v125
	v_mul_f32_e32 v124, v117, v117
	v_mul_f32_e32 v125, v119, v119
	v_fmac_f32_e32 v124, v116, v116
	v_fmac_f32_e32 v125, v118, v118
	v_add_f32_e32 v124, v124, v125
	v_mul_f32_e32 v125, v113, v113
	v_fmac_f32_e32 v125, v112, v112
	v_add_f32_e32 v124, v124, v125
	v_mul_f32_e32 v125, v115, v115
	v_fmac_f32_e32 v125, v114, v114
	v_cvt_pk_bf16_f32 v157, v126, v127
	v_add_f32_e32 v124, v125, v124
	v_and_b32_e32 v126, 64, v154
	v_add_f32_e32 v125, v155, v124
	v_xor_b32_e32 v124, 16, v154
	v_add_u32_e32 v126, 64, v126
	v_cmp_lt_i32_e32 vcc, v124, v126
	v_cvt_pk_bf16_f32 v158, v120, v121
	v_cvt_pk_bf16_f32 v159, v122, v123
	global_store_dwordx4 v[160:161], v[156:159], off sc1
	s_lshl_b32 s28, s8, 2
	v_cndmask_b32_e32 v124, v154, v124, vcc
	v_lshlrev_b32_e32 v124, 2, v124
	ds_bpermute_b32 v127, v124, v125
	v_cvt_pk_bf16_f32 v156, v116, v117
	v_xor_b32_e32 v116, 32, v154
	v_cmp_lt_i32_e32 vcc, v116, v126
	s_ashr_i32 s29, s28, 31
	s_waitcnt lgkmcnt(0)
	v_add_f32_e32 v117, v125, v127
	v_cndmask_b32_e32 v116, v154, v116, vcc
	v_lshlrev_b32_e32 v116, 2, v116
	ds_bpermute_b32 v120, v116, v117
	v_cvt_pk_bf16_f32 v157, v118, v119
	v_cvt_pk_bf16_f32 v158, v112, v113
	v_cvt_pk_bf16_f32 v159, v114, v115
	global_store_dwordx4 v[160:161], v[156:159], off offset:256 sc1
	s_and_saveexec_b64 s[30:31], s[0:1]
	s_cbranch_execz .LBB0_1200
	v_lshlrev_b64 v[112:113], 7, v[146:147]
	v_lshl_add_u64 v[112:113], s[14:15], 0, v[112:113]
	v_lshl_add_u64 v[112:113], s[28:29], 2, v[112:113]
	s_lshl_b32 s8, s56, 2
	v_lshl_add_u64 v[112:113], v[112:113], 0, s[8:9]
	s_waitcnt lgkmcnt(0)
	v_add_f32_e32 v114, v117, v120
	global_store_dword v[112:113], v114, off
.LBB0_1200:
	s_or_b64 exec, exec, s[30:31]
	v_mul_f32_e32 v117, v109, v109
	v_mul_f32_e32 v118, v111, v111
	v_fmac_f32_e32 v117, v108, v108
	v_fmac_f32_e32 v118, v110, v110
	v_cvt_pk_bf16_f32 v108, v108, v109
	v_cvt_pk_bf16_f32 v109, v110, v111
	v_mul_f32_e32 v110, v101, v101
	v_mul_f32_e32 v111, v103, v103
	v_fmac_f32_e32 v110, v100, v100
	v_fmac_f32_e32 v111, v102, v102
	v_add_f32_e32 v117, v117, v118
	v_mul_f32_e32 v118, v105, v105
	v_add_f32_e32 v110, v110, v111
	v_mul_f32_e32 v111, v97, v97
	v_fmac_f32_e32 v118, v104, v104
	v_fmac_f32_e32 v111, v96, v96
	v_add_f32_e32 v117, v117, v118
	v_mul_f32_e32 v118, v107, v107
	v_add_f32_e32 v110, v110, v111
	v_mul_f32_e32 v111, v99, v99
	v_fmac_f32_e32 v118, v106, v106
	v_fmac_f32_e32 v111, v98, v98
	v_add_f32_e32 v117, v118, v117
	v_add_f32_e32 v110, v111, v110
	v_add_f32_e32 v117, v117, v110
	v_or_b32_e32 v112, 16, v146
	ds_bpermute_b32 v118, v124, v117
	v_ashrrev_i32_e32 v113, 31, v112
	v_lshlrev_b64 v[114:115], 12, v[112:113]
	v_lshl_add_u64 v[114:115], s[12:13], 0, v[114:115]
	v_lshl_add_u64 v[114:115], v[144:145], 1, v[114:115]
	v_cvt_pk_bf16_f32 v110, v104, v105
	v_cvt_pk_bf16_f32 v111, v106, v107
	global_store_dwordx4 v[114:115], v[108:111], off sc1
	v_cvt_pk_bf16_f32 v104, v100, v101
	s_waitcnt lgkmcnt(0)
	v_add_f32_e32 v100, v117, v118
	ds_bpermute_b32 v101, v116, v100
	v_cvt_pk_bf16_f32 v105, v102, v103
	v_cvt_pk_bf16_f32 v106, v96, v97
	v_cvt_pk_bf16_f32 v107, v98, v99
	global_store_dwordx4 v[114:115], v[104:107], off offset:256 sc1
	s_and_saveexec_b64 s[30:31], s[0:1]
	s_cbranch_execz .LBB0_1202
	v_lshlrev_b64 v[96:97], 7, v[112:113]
	v_lshl_add_u64 v[96:97], s[14:15], 0, v[96:97]
	v_lshl_add_u64 v[96:97], s[28:29], 2, v[96:97]
	s_lshl_b32 s8, s56, 2
	v_lshl_add_u64 v[96:97], v[96:97], 0, s[8:9]
	s_waitcnt lgkmcnt(0)
	v_add_f32_e32 v98, v100, v101
	global_store_dword v[96:97], v98, off
.LBB0_1202:
	s_or_b64 exec, exec, s[30:31]
	v_mul_f32_e32 v100, v93, v93
	s_waitcnt lgkmcnt(0)
	v_mul_f32_e32 v101, v95, v95
	v_fmac_f32_e32 v100, v92, v92
	v_fmac_f32_e32 v101, v94, v94
	v_cvt_pk_bf16_f32 v92, v92, v93
	v_cvt_pk_bf16_f32 v93, v94, v95
	v_mul_f32_e32 v94, v85, v85
	v_mul_f32_e32 v95, v87, v87
	v_fmac_f32_e32 v94, v84, v84
	v_fmac_f32_e32 v95, v86, v86
	v_add_f32_e32 v100, v100, v101
	v_mul_f32_e32 v101, v89, v89
	v_add_f32_e32 v94, v94, v95
	v_mul_f32_e32 v95, v81, v81
	v_fmac_f32_e32 v101, v88, v88
	v_fmac_f32_e32 v95, v80, v80
	v_add_f32_e32 v100, v100, v101
	v_mul_f32_e32 v101, v91, v91
	v_add_f32_e32 v94, v94, v95
	v_mul_f32_e32 v95, v83, v83
	v_fmac_f32_e32 v101, v90, v90
	v_fmac_f32_e32 v95, v82, v82
	v_add_f32_e32 v100, v101, v100
	v_add_f32_e32 v94, v95, v94
	v_add_f32_e32 v100, v100, v94
	v_or_b32_e32 v96, 32, v146
	ds_bpermute_b32 v101, v124, v100
	v_ashrrev_i32_e32 v97, 31, v96
	v_lshlrev_b64 v[98:99], 12, v[96:97]
	v_lshl_add_u64 v[98:99], s[12:13], 0, v[98:99]
	v_lshl_add_u64 v[98:99], v[144:145], 1, v[98:99]
	v_cvt_pk_bf16_f32 v94, v88, v89
	v_cvt_pk_bf16_f32 v95, v90, v91
	global_store_dwordx4 v[98:99], v[92:95], off sc1
	v_cvt_pk_bf16_f32 v88, v84, v85
	s_waitcnt lgkmcnt(0)
	v_add_f32_e32 v84, v100, v101
	ds_bpermute_b32 v85, v116, v84
	v_cvt_pk_bf16_f32 v89, v86, v87
	v_cvt_pk_bf16_f32 v90, v80, v81
	v_cvt_pk_bf16_f32 v91, v82, v83
	global_store_dwordx4 v[98:99], v[88:91], off offset:256 sc1
	s_and_saveexec_b64 s[30:31], s[0:1]
	s_cbranch_execz .LBB0_1204
	v_lshlrev_b64 v[80:81], 7, v[96:97]
	v_lshl_add_u64 v[80:81], s[14:15], 0, v[80:81]
	v_lshl_add_u64 v[80:81], s[28:29], 2, v[80:81]
	s_lshl_b32 s8, s56, 2
	v_lshl_add_u64 v[80:81], v[80:81], 0, s[8:9]
	s_waitcnt lgkmcnt(0)
	v_add_f32_e32 v82, v84, v85
	global_store_dword v[80:81], v82, off
; __device__ __forceinline__ unsigned cvt_pk_bf16(float lo, float hi) { unsigned r; asm volatile("v_cvt_pk_bf16_f32 %0, %1, %2" : "=v"(r) : "v"(lo), "v"(hi)); return r; }
;     __device__ __forceinline__ void operator()(const f32x4 (&acc)[2][2][4][2], const Unit& u, int wr, int wc, int fr, int fq) const {
;     ...
;         for (int ai = 0; ai < 2; ++ai)
; #pragma unroll
;             for (int m = 0; m < 4; ++m) { const int r = row0 + ai * HALF + m * 16; bf16_t* rowp = C + (size_t)r * ldc + col0; float s = 0.f;
; #pragma unroll
;                 for (int bj = 0; bj < 2; ++bj) { const f32x4 v0 = acc[ai][bj][m][0], v1 = acc[ai][bj][m][1];
;                     s += (v0[0] * v0[0] + v0[1] * v0[1]) + (v0[2] * v0[2] + v0[3] * v0[3]) + (v1[0] * v1[0] + v1[1] * v1[1]) + (v1[2] * v1[2] + v1[3] * v1[3]);
;                     u32x4 w; w.x = cvt_pk_bf16(v0[0], v0[1]); w.y = cvt_pk_bf16(v0[2], v0[3]); w.z = cvt_pk_bf16(v1[0], v1[1]); w.w = cvt_pk_bf16(v1[2], v1[3]);
;                     *(u32x4*)(rowp + bj * HALF) = w; }
;                 s += __shfl_xor(s, 16); s += __shfl_xor(s, 32);
;                 if (fq == 0) ssq[(size_t)r * 32 + u.pn * 4 + wc] = s; }
.LBB0_1204:
	s_or_b64 exec, exec, s[30:31]
	v_mul_f32_e32 v84, v77, v77
	s_waitcnt lgkmcnt(0)
	v_mul_f32_e32 v85, v79, v79
	v_fmac_f32_e32 v84, v76, v76
	v_fmac_f32_e32 v85, v78, v78
	v_cvt_pk_bf16_f32 v76, v76, v77
	v_cvt_pk_bf16_f32 v77, v78, v79
	v_mul_f32_e32 v78, v69, v69
	v_mul_f32_e32 v79, v71, v71
	v_fmac_f32_e32 v78, v68, v68
	v_fmac_f32_e32 v79, v70, v70
	v_add_f32_e32 v84, v84, v85
	v_mul_f32_e32 v85, v73, v73
	v_add_f32_e32 v78, v78, v79
	v_mul_f32_e32 v79, v65, v65
	v_fmac_f32_e32 v85, v72, v72
	v_fmac_f32_e32 v79, v64, v64
	v_add_f32_e32 v84, v84, v85
	v_mul_f32_e32 v85, v75, v75
	v_add_f32_e32 v78, v78, v79
	v_mul_f32_e32 v79, v67, v67
	v_fmac_f32_e32 v85, v74, v74
	v_fmac_f32_e32 v79, v66, v66
	v_add_f32_e32 v84, v85, v84
	v_add_f32_e32 v78, v79, v78
	v_add_f32_e32 v84, v84, v78
	v_or_b32_e32 v80, 48, v146
	ds_bpermute_b32 v85, v124, v84
	v_ashrrev_i32_e32 v81, 31, v80
	v_lshlrev_b64 v[82:83], 12, v[80:81]
	v_lshl_add_u64 v[82:83], s[12:13], 0, v[82:83]
	v_lshl_add_u64 v[82:83], v[144:145], 1, v[82:83]
	v_cvt_pk_bf16_f32 v78, v72, v73
	v_cvt_pk_bf16_f32 v79, v74, v75
	global_store_dwordx4 v[82:83], v[76:79], off sc1
	v_cvt_pk_bf16_f32 v72, v68, v69
	s_waitcnt lgkmcnt(0)
	v_add_f32_e32 v68, v84, v85
	ds_bpermute_b32 v69, v116, v68
	v_cvt_pk_bf16_f32 v73, v70, v71
	v_cvt_pk_bf16_f32 v74, v64, v65
	v_cvt_pk_bf16_f32 v75, v66, v67
	global_store_dwordx4 v[82:83], v[72:75], off offset:256 sc1
	s_and_saveexec_b64 s[30:31], s[0:1]
	s_cbranch_execz .LBB0_1206
	v_lshlrev_b64 v[64:65], 7, v[80:81]
	v_lshl_add_u64 v[64:65], s[14:15], 0, v[64:65]
	v_lshl_add_u64 v[64:65], s[28:29], 2, v[64:65]
	s_lshl_b32 s8, s56, 2
	v_lshl_add_u64 v[64:65], v[64:65], 0, s[8:9]
	s_waitcnt lgkmcnt(0)
	v_add_f32_e32 v66, v68, v69
	global_store_dword v[64:65], v66, off
.LBB0_1206:
	s_or_b64 exec, exec, s[30:31]
	v_mul_f32_e32 v68, v61, v61
	s_waitcnt lgkmcnt(0)
	v_mul_f32_e32 v69, v63, v63
	v_fmac_f32_e32 v68, v60, v60
	v_fmac_f32_e32 v69, v62, v62
	v_cvt_pk_bf16_f32 v60, v60, v61
	v_cvt_pk_bf16_f32 v61, v62, v63
	v_mul_f32_e32 v62, v53, v53
	v_mul_f32_e32 v63, v55, v55
	v_fmac_f32_e32 v62, v52, v52
	v_fmac_f32_e32 v63, v54, v54
	v_add_f32_e32 v68, v68, v69
	v_mul_f32_e32 v69, v57, v57
	v_add_f32_e32 v62, v62, v63
	v_mul_f32_e32 v63, v49, v49
	v_fmac_f32_e32 v69, v56, v56
	v_fmac_f32_e32 v63, v48, v48
	v_add_f32_e32 v68, v68, v69
	v_mul_f32_e32 v69, v59, v59
	v_add_f32_e32 v62, v62, v63
	v_mul_f32_e32 v63, v51, v51
	v_fmac_f32_e32 v69, v58, v58
	v_fmac_f32_e32 v63, v50, v50
	v_add_f32_e32 v68, v69, v68
	v_add_f32_e32 v62, v63, v62
	v_add_f32_e32 v68, v68, v62
	v_add_u32_e32 v64, 0x80, v146
	ds_bpermute_b32 v69, v124, v68
	v_ashrrev_i32_e32 v65, 31, v64
	v_lshlrev_b64 v[66:67], 12, v[64:65]
	v_lshl_add_u64 v[66:67], s[12:13], 0, v[66:67]
	v_lshl_add_u64 v[66:67], v[144:145], 1, v[66:67]
	v_cvt_pk_bf16_f32 v62, v56, v57
	v_cvt_pk_bf16_f32 v63, v58, v59
	global_store_dwordx4 v[66:67], v[60:63], off sc1
	v_cvt_pk_bf16_f32 v56, v52, v53
	s_waitcnt lgkmcnt(0)
	v_add_f32_e32 v52, v68, v69
	ds_bpermute_b32 v53, v116, v52
	v_cvt_pk_bf16_f32 v57, v54, v55
	v_cvt_pk_bf16_f32 v58, v48, v49
	v_cvt_pk_bf16_f32 v59, v50, v51
	global_store_dwordx4 v[66:67], v[56:59], off offset:256 sc1
	s_and_saveexec_b64 s[30:31], s[0:1]
	s_cbranch_execz .LBB0_1208
	v_lshlrev_b64 v[48:49], 7, v[64:65]
	v_lshl_add_u64 v[48:49], s[14:15], 0, v[48:49]
	v_lshl_add_u64 v[48:49], s[28:29], 2, v[48:49]
	s_lshl_b32 s8, s56, 2
	v_lshl_add_u64 v[48:49], v[48:49], 0, s[8:9]
	s_waitcnt lgkmcnt(0)
	v_add_f32_e32 v50, v52, v53
	global_store_dword v[48:49], v50, off
; __device__ __forceinline__ unsigned cvt_pk_bf16(float lo, float hi) { unsigned r; asm volatile("v_cvt_pk_bf16_f32 %0, %1, %2" : "=v"(r) : "v"(lo), "v"(hi)); return r; }
;     __device__ __forceinline__ void operator()(const f32x4 (&acc)[2][2][4][2], const Unit& u, int wr, int wc, int fr, int fq) const {
;     ...
;         for (int ai = 0; ai < 2; ++ai)
; #pragma unroll
;             for (int m = 0; m < 4; ++m) { const int r = row0 + ai * HALF + m * 16; bf16_t* rowp = C + (size_t)r * ldc + col0; float s = 0.f;
; #pragma unroll
;                 for (int bj = 0; bj < 2; ++bj) { const f32x4 v0 = acc[ai][bj][m][0], v1 = acc[ai][bj][m][1];
;                     s += (v0[0] * v0[0] + v0[1] * v0[1]) + (v0[2] * v0[2] + v0[3] * v0[3]) + (v1[0] * v1[0] + v1[1] * v1[1]) + (v1[2] * v1[2] + v1[3] * v1[3]);
;                     u32x4 w; w.x = cvt_pk_bf16(v0[0], v0[1]); w.y = cvt_pk_bf16(v0[2], v0[3]); w.z = cvt_pk_bf16(v1[0], v1[1]); w.w = cvt_pk_bf16(v1[2], v1[3]);
;                     *(u32x4*)(rowp + bj * HALF) = w; }
;                 s += __shfl_xor(s, 16); s += __shfl_xor(s, 32);
;                 if (fq == 0) ssq[(size_t)r * 32 + u.pn * 4 + wc] = s; }
.LBB0_1208:
	s_or_b64 exec, exec, s[30:31]
	v_mul_f32_e32 v52, v45, v45
	s_waitcnt lgkmcnt(0)
	v_mul_f32_e32 v53, v47, v47
	v_fmac_f32_e32 v52, v44, v44
	v_fmac_f32_e32 v53, v46, v46
	v_cvt_pk_bf16_f32 v44, v44, v45
	v_cvt_pk_bf16_f32 v45, v46, v47
	v_mul_f32_e32 v46, v37, v37
	v_mul_f32_e32 v47, v39, v39
	v_fmac_f32_e32 v46, v36, v36
	v_fmac_f32_e32 v47, v38, v38
	v_add_f32_e32 v52, v52, v53
	v_mul_f32_e32 v53, v41, v41
	v_add_f32_e32 v46, v46, v47
	v_mul_f32_e32 v47, v33, v33
	v_fmac_f32_e32 v53, v40, v40
	v_fmac_f32_e32 v47, v32, v32
	v_add_f32_e32 v52, v52, v53
	v_mul_f32_e32 v53, v43, v43
	v_add_f32_e32 v46, v46, v47
	v_mul_f32_e32 v47, v35, v35
	v_fmac_f32_e32 v53, v42, v42
	v_fmac_f32_e32 v47, v34, v34
	v_add_f32_e32 v52, v53, v52
	v_add_f32_e32 v46, v47, v46
	v_add_f32_e32 v52, v52, v46
	v_add_u32_e32 v48, 0x90, v146
	ds_bpermute_b32 v53, v124, v52
	v_ashrrev_i32_e32 v49, 31, v48
	v_lshlrev_b64 v[50:51], 12, v[48:49]
	v_lshl_add_u64 v[50:51], s[12:13], 0, v[50:51]
	v_lshl_add_u64 v[50:51], v[144:145], 1, v[50:51]
	v_cvt_pk_bf16_f32 v46, v40, v41
	v_cvt_pk_bf16_f32 v47, v42, v43
	global_store_dwordx4 v[50:51], v[44:47], off sc1
	v_cvt_pk_bf16_f32 v40, v36, v37
	s_waitcnt lgkmcnt(0)
	v_add_f32_e32 v36, v52, v53
	ds_bpermute_b32 v37, v116, v36
	v_cvt_pk_bf16_f32 v41, v38, v39
	v_cvt_pk_bf16_f32 v42, v32, v33
	v_cvt_pk_bf16_f32 v43, v34, v35
	global_store_dwordx4 v[50:51], v[40:43], off offset:256 sc1
	s_and_saveexec_b64 s[30:31], s[0:1]
	s_cbranch_execz .LBB0_1210
	v_lshlrev_b64 v[32:33], 7, v[48:49]
	v_lshl_add_u64 v[32:33], s[14:15], 0, v[32:33]
	v_lshl_add_u64 v[32:33], s[28:29], 2, v[32:33]
	s_lshl_b32 s8, s56, 2
	v_lshl_add_u64 v[32:33], v[32:33], 0, s[8:9]
	s_waitcnt lgkmcnt(0)
	v_add_f32_e32 v34, v36, v37
	global_store_dword v[32:33], v34, off
.LBB0_1210:
	s_or_b64 exec, exec, s[30:31]
	v_mul_f32_e32 v36, v29, v29
	s_waitcnt lgkmcnt(0)
	v_mul_f32_e32 v37, v31, v31
	v_fmac_f32_e32 v36, v28, v28
	v_fmac_f32_e32 v37, v30, v30
	v_cvt_pk_bf16_f32 v28, v28, v29
	v_cvt_pk_bf16_f32 v29, v30, v31
	v_mul_f32_e32 v30, v21, v21
	v_mul_f32_e32 v31, v23, v23
	v_fmac_f32_e32 v30, v20, v20
	v_fmac_f32_e32 v31, v22, v22
	v_add_f32_e32 v36, v36, v37
	v_mul_f32_e32 v37, v25, v25
	v_add_f32_e32 v30, v30, v31
	v_mul_f32_e32 v31, v17, v17
	v_fmac_f32_e32 v37, v24, v24
	v_fmac_f32_e32 v31, v16, v16
	v_add_f32_e32 v36, v36, v37
	v_mul_f32_e32 v37, v27, v27
	v_add_f32_e32 v30, v30, v31
	v_mul_f32_e32 v31, v19, v19
	v_fmac_f32_e32 v37, v26, v26
	v_fmac_f32_e32 v31, v18, v18
	v_add_f32_e32 v36, v37, v36
	v_add_f32_e32 v30, v31, v30
	v_add_f32_e32 v36, v36, v30
	v_add_u32_e32 v32, 0xa0, v146
	ds_bpermute_b32 v37, v124, v36
	v_ashrrev_i32_e32 v33, 31, v32
	v_lshlrev_b64 v[34:35], 12, v[32:33]
	v_lshl_add_u64 v[34:35], s[12:13], 0, v[34:35]
	v_lshl_add_u64 v[34:35], v[144:145], 1, v[34:35]
	v_cvt_pk_bf16_f32 v30, v24, v25
	v_cvt_pk_bf16_f32 v31, v26, v27
	global_store_dwordx4 v[34:35], v[28:31], off sc1
	v_cvt_pk_bf16_f32 v24, v20, v21
	s_waitcnt lgkmcnt(0)
	v_add_f32_e32 v20, v36, v37
	ds_bpermute_b32 v21, v116, v20
	v_cvt_pk_bf16_f32 v25, v22, v23
	v_cvt_pk_bf16_f32 v26, v16, v17
	v_cvt_pk_bf16_f32 v27, v18, v19
	global_store_dwordx4 v[34:35], v[24:27], off offset:256 sc1
	s_and_saveexec_b64 s[30:31], s[0:1]
	s_cbranch_execz .LBB0_1212
	v_lshlrev_b64 v[16:17], 7, v[32:33]
	v_lshl_add_u64 v[16:17], s[14:15], 0, v[16:17]
	v_lshl_add_u64 v[16:17], s[28:29], 2, v[16:17]
	s_lshl_b32 s8, s56, 2
	v_lshl_add_u64 v[16:17], v[16:17], 0, s[8:9]
	s_waitcnt lgkmcnt(0)
	v_add_f32_e32 v18, v20, v21
	global_store_dword v[16:17], v18, off
.LBB0_1212:
	s_or_b64 exec, exec, s[30:31]
	v_mul_f32_e32 v20, v13, v13
	s_waitcnt lgkmcnt(0)
	v_mul_f32_e32 v21, v15, v15
	v_fmac_f32_e32 v20, v12, v12
	v_fmac_f32_e32 v21, v14, v14
	v_cvt_pk_bf16_f32 v12, v12, v13
	v_cvt_pk_bf16_f32 v13, v14, v15
	v_mul_f32_e32 v14, v5, v5
	v_mul_f32_e32 v15, v7, v7
	v_fmac_f32_e32 v14, v4, v4
	v_fmac_f32_e32 v15, v6, v6
	v_add_f32_e32 v20, v20, v21
	v_mul_f32_e32 v21, v9, v9
	v_add_f32_e32 v14, v14, v15
	v_mul_f32_e32 v15, v1, v1
	v_fmac_f32_e32 v21, v8, v8
	v_fmac_f32_e32 v15, v0, v0
	v_add_f32_e32 v20, v20, v21
	v_mul_f32_e32 v21, v11, v11
	v_add_f32_e32 v14, v14, v15
	v_mul_f32_e32 v15, v3, v3
	v_fmac_f32_e32 v21, v10, v10
	v_fmac_f32_e32 v15, v2, v2
	v_add_f32_e32 v20, v21, v20
	v_add_f32_e32 v14, v15, v14
	v_add_f32_e32 v20, v20, v14
	v_add_u32_e32 v16, 0xb0, v146
	ds_bpermute_b32 v21, v124, v20
	v_ashrrev_i32_e32 v17, 31, v16
	v_lshlrev_b64 v[18:19], 12, v[16:17]
	v_lshl_add_u64 v[18:19], s[12:13], 0, v[18:19]
	v_lshl_add_u64 v[18:19], v[144:145], 1, v[18:19]
	v_cvt_pk_bf16_f32 v14, v8, v9
	v_cvt_pk_bf16_f32 v15, v10, v11
	global_store_dwordx4 v[18:19], v[12:15], off sc1
	v_cvt_pk_bf16_f32 v8, v4, v5
	s_waitcnt lgkmcnt(0)
	v_add_f32_e32 v4, v20, v21
	ds_bpermute_b32 v5, v116, v4
	v_cvt_pk_bf16_f32 v9, v6, v7
	v_cvt_pk_bf16_f32 v10, v0, v1
	v_cvt_pk_bf16_f32 v11, v2, v3
	global_store_dwordx4 v[18:19], v[8:11], off offset:256 sc1
	s_and_saveexec_b64 s[30:31], s[0:1]
	s_cbranch_execz .LBB0_1214
	v_lshlrev_b64 v[0:1], 7, v[16:17]
	v_lshl_add_u64 v[0:1], s[14:15], 0, v[0:1]
	v_lshl_add_u64 v[0:1], s[28:29], 2, v[0:1]
	s_lshl_b32 s8, s56, 2
	v_lshl_add_u64 v[0:1], v[0:1], 0, s[8:9]
	s_waitcnt lgkmcnt(0)
	v_add_f32_e32 v2, v4, v5
	global_store_dword v[0:1], v2, off

; __device__ __forceinline__ unsigned cvt_pk_bf16(float lo, float hi) { unsigned r; asm volatile("v_cvt_pk_bf16_f32 %0, %1, %2" : "=v"(r) : "v"(lo), "v"(hi)); return r; }
;     __device__ __forceinline__ void operator()(const f32x4 (&acc)[2][2][4][2], const Unit& u, int wr, int wc, int fr, int fq) const {
;         const int row0 = u.pm * BM + wr * 64 + fr, col0 = u.pn * BM + wc * 32 + 8 * fq;
; #pragma unroll
;         for (int ai = 0; ai < 2; ++ai)
; #pragma unroll
;             for (int m = 0; m < 4; ++m) { const int r = row0 + ai * HALF + m * 16; bf16_t* rowp = C + (size_t)r * ldc + col0; float s = 0.f;
; #pragma unroll
;                 for (int bj = 0; bj < 2; ++bj) { const f32x4 v0 = acc[ai][bj][m][0], v1 = acc[ai][bj][m][1];
;                     s += (v0[0] * v0[0] + v0[1] * v0[1]) + (v0[2] * v0[2] + v0[3] * v0[3]) + (v1[0] * v1[0] + v1[1] * v1[1]) + (v1[2] * v1[2] + v1[3] * v1[3]);
;                     u32x4 w; w.x = cvt_pk_bf16(v0[0], v0[1]); w.y = cvt_pk_bf16(v0[2], v0[3]); w.z = cvt_pk_bf16(v1[0], v1[1]); w.w = cvt_pk_bf16(v1[2], v1[3]);
;                     *(u32x4*)(rowp + bj * HALF) = w; }
;                 s += __shfl_xor(s, 16); s += __shfl_xor(s, 32);
;                 if (fq == 0) ssq[(size_t)r * 32 + u.pn * 4 + wc] = s; }
.LBB0_1420:
	v_lshl_add_u32 v146, s54, 8, v148
	v_ashrrev_i32_e32 v147, 31, v146
	v_lshl_or_b32 v144, s10, 8, v150
	v_lshlrev_b64 v[156:157], 12, v[146:147]
	v_ashrrev_i32_e32 v145, 31, v144
	v_lshl_add_u64 v[156:157], s[14:15], 0, v[156:157]
	v_lshl_add_u64 v[160:161], v[144:145], 1, v[156:157]
	v_mul_f32_e32 v155, v125, v125
	v_mul_f32_e32 v156, v127, v127
	v_fmac_f32_e32 v155, v124, v124
	v_fmac_f32_e32 v156, v126, v126
	v_add_f32_e32 v155, v155, v156
	v_mul_f32_e32 v156, v121, v121
	v_fmac_f32_e32 v156, v120, v120
	v_add_f32_e32 v155, v155, v156
	v_mul_f32_e32 v156, v123, v123
	v_fmac_f32_e32 v156, v122, v122
	v_add_f32_e32 v155, v156, v155
	v_cvt_pk_bf16_f32 v156, v124, v125
	v_mul_f32_e32 v124, v117, v117
	v_mul_f32_e32 v125, v119, v119
	v_fmac_f32_e32 v124, v116, v116
	v_fmac_f32_e32 v125, v118, v118
	v_add_f32_e32 v124, v124, v125
	v_mul_f32_e32 v125, v113, v113
	v_fmac_f32_e32 v125, v112, v112
	v_add_f32_e32 v124, v124, v125
	v_mul_f32_e32 v125, v115, v115
	v_fmac_f32_e32 v125, v114, v114
	v_cvt_pk_bf16_f32 v157, v126, v127
	v_add_f32_e32 v124, v125, v124
	v_and_b32_e32 v126, 64, v154
	v_add_f32_e32 v125, v155, v124
	v_xor_b32_e32 v124, 16, v154
	v_add_u32_e32 v126, 64, v126
	v_cmp_lt_i32_e32 vcc, v124, v126
	v_cvt_pk_bf16_f32 v158, v120, v121
	v_cvt_pk_bf16_f32 v159, v122, v123
	global_store_dwordx4 v[160:161], v[156:159], off sc1
	s_lshl_b32 s24, s10, 2
	v_cndmask_b32_e32 v124, v154, v124, vcc
	v_lshlrev_b32_e32 v124, 2, v124
	ds_bpermute_b32 v127, v124, v125
	v_cvt_pk_bf16_f32 v156, v116, v117
	v_xor_b32_e32 v116, 32, v154
	v_cmp_lt_i32_e32 vcc, v116, v126
	s_ashr_i32 s25, s24, 31
	s_waitcnt lgkmcnt(0)
	v_add_f32_e32 v117, v125, v127
	v_cndmask_b32_e32 v116, v154, v116, vcc
	v_lshlrev_b32_e32 v116, 2, v116
	ds_bpermute_b32 v120, v116, v117
	v_cvt_pk_bf16_f32 v157, v118, v119
	v_cvt_pk_bf16_f32 v158, v112, v113
	v_cvt_pk_bf16_f32 v159, v114, v115
	global_store_dwordx4 v[160:161], v[156:159], off offset:256 sc1
	s_and_saveexec_b64 s[26:27], s[0:1]
	s_cbranch_execz .LBB0_1422
	v_lshlrev_b64 v[112:113], 7, v[146:147]
	v_lshl_add_u64 v[112:113], s[16:17], 0, v[112:113]
	v_lshl_add_u64 v[112:113], s[24:25], 2, v[112:113]
	s_lshl_b32 s10, s40, 2
	v_lshl_add_u64 v[112:113], v[112:113], 0, s[10:11]
	s_waitcnt lgkmcnt(0)
	v_add_f32_e32 v114, v117, v120
	global_store_dword v[112:113], v114, off
.LBB0_1422:
	s_or_b64 exec, exec, s[26:27]
	v_mul_f32_e32 v117, v109, v109
	v_mul_f32_e32 v118, v111, v111
	v_fmac_f32_e32 v117, v108, v108
	v_fmac_f32_e32 v118, v110, v110
	v_cvt_pk_bf16_f32 v108, v108, v109
	v_cvt_pk_bf16_f32 v109, v110, v111
	v_mul_f32_e32 v110, v101, v101
	v_mul_f32_e32 v111, v103, v103
	v_fmac_f32_e32 v110, v100, v100
	v_fmac_f32_e32 v111, v102, v102
	v_add_f32_e32 v117, v117, v118
	v_mul_f32_e32 v118, v105, v105
	v_add_f32_e32 v110, v110, v111
	v_mul_f32_e32 v111, v97, v97
	v_fmac_f32_e32 v118, v104, v104
	v_fmac_f32_e32 v111, v96, v96
	v_add_f32_e32 v117, v117, v118
	v_mul_f32_e32 v118, v107, v107
	v_add_f32_e32 v110, v110, v111
	v_mul_f32_e32 v111, v99, v99
	v_fmac_f32_e32 v118, v106, v106
	v_fmac_f32_e32 v111, v98, v98
	v_add_f32_e32 v117, v118, v117
	v_add_f32_e32 v110, v111, v110
	v_add_f32_e32 v117, v117, v110
	v_or_b32_e32 v112, 16, v146
	ds_bpermute_b32 v118, v124, v117
	v_ashrrev_i32_e32 v113, 31, v112
	v_lshlrev_b64 v[114:115], 12, v[112:113]
	v_lshl_add_u64 v[114:115], s[14:15], 0, v[114:115]
	v_lshl_add_u64 v[114:115], v[144:145], 1, v[114:115]
	v_cvt_pk_bf16_f32 v110, v104, v105
	v_cvt_pk_bf16_f32 v111, v106, v107
	global_store_dwordx4 v[114:115], v[108:111], off sc1
	v_cvt_pk_bf16_f32 v104, v100, v101
	s_waitcnt lgkmcnt(0)
	v_add_f32_e32 v100, v117, v118
	ds_bpermute_b32 v101, v116, v100
	v_cvt_pk_bf16_f32 v105, v102, v103
	v_cvt_pk_bf16_f32 v106, v96, v97
	v_cvt_pk_bf16_f32 v107, v98, v99
	global_store_dwordx4 v[114:115], v[104:107], off offset:256 sc1
	s_and_saveexec_b64 s[26:27], s[0:1]
	s_cbranch_execz .LBB0_1424
	v_lshlrev_b64 v[96:97], 7, v[112:113]
	v_lshl_add_u64 v[96:97], s[16:17], 0, v[96:97]
	v_lshl_add_u64 v[96:97], s[24:25], 2, v[96:97]
	s_lshl_b32 s10, s40, 2
	v_lshl_add_u64 v[96:97], v[96:97], 0, s[10:11]
	s_waitcnt lgkmcnt(0)
	v_add_f32_e32 v98, v100, v101
	global_store_dword v[96:97], v98, off
.LBB0_1424:
	s_or_b64 exec, exec, s[26:27]
	v_mul_f32_e32 v100, v93, v93
	s_waitcnt lgkmcnt(0)
	v_mul_f32_e32 v101, v95, v95
	v_fmac_f32_e32 v100, v92, v92
	v_fmac_f32_e32 v101, v94, v94
	v_cvt_pk_bf16_f32 v92, v92, v93
	v_cvt_pk_bf16_f32 v93, v94, v95
	v_mul_f32_e32 v94, v85, v85
	v_mul_f32_e32 v95, v87, v87
	v_fmac_f32_e32 v94, v84, v84
	v_fmac_f32_e32 v95, v86, v86
	v_add_f32_e32 v100, v100, v101
	v_mul_f32_e32 v101, v89, v89
	v_add_f32_e32 v94, v94, v95
	v_mul_f32_e32 v95, v81, v81
	v_fmac_f32_e32 v101, v88, v88
	v_fmac_f32_e32 v95, v80, v80
	v_add_f32_e32 v100, v100, v101
	v_mul_f32_e32 v101, v91, v91
	v_add_f32_e32 v94, v94, v95
	v_mul_f32_e32 v95, v83, v83
	v_fmac_f32_e32 v101, v90, v90
	v_fmac_f32_e32 v95, v82, v82
	v_add_f32_e32 v100, v101, v100
	v_add_f32_e32 v94, v95, v94
	v_add_f32_e32 v100, v100, v94
	v_or_b32_e32 v96, 32, v146
	ds_bpermute_b32 v101, v124, v100
	v_ashrrev_i32_e32 v97, 31, v96
	v_lshlrev_b64 v[98:99], 12, v[96:97]
	v_lshl_add_u64 v[98:99], s[14:15], 0, v[98:99]
	v_lshl_add_u64 v[98:99], v[144:145], 1, v[98:99]
	v_cvt_pk_bf16_f32 v94, v88, v89
	v_cvt_pk_bf16_f32 v95, v90, v91
	global_store_dwordx4 v[98:99], v[92:95], off sc1
	v_cvt_pk_bf16_f32 v88, v84, v85
	s_waitcnt lgkmcnt(0)
	v_add_f32_e32 v84, v100, v101
	ds_bpermute_b32 v85, v116, v84
	v_cvt_pk_bf16_f32 v89, v86, v87
	v_cvt_pk_bf16_f32 v90, v80, v81
	v_cvt_pk_bf16_f32 v91, v82, v83
	global_store_dwordx4 v[98:99], v[88:91], off offset:256 sc1
	s_and_saveexec_b64 s[26:27], s[0:1]
	s_cbranch_execz .LBB0_1426
	v_lshlrev_b64 v[80:81], 7, v[96:97]
	v_lshl_add_u64 v[80:81], s[16:17], 0, v[80:81]
	v_lshl_add_u64 v[80:81], s[24:25], 2, v[80:81]
	s_lshl_b32 s10, s40, 2
	v_lshl_add_u64 v[80:81], v[80:81], 0, s[10:11]
	s_waitcnt lgkmcnt(0)
	v_add_f32_e32 v82, v84, v85
	global_store_dword v[80:81], v82, off
; __device__ __forceinline__ unsigned cvt_pk_bf16(float lo, float hi) { unsigned r; asm volatile("v_cvt_pk_bf16_f32 %0, %1, %2" : "=v"(r) : "v"(lo), "v"(hi)); return r; }
;     __device__ __forceinline__ void operator()(const f32x4 (&acc)[2][2][4][2], const Unit& u, int wr, int wc, int fr, int fq) const {
;     ...
;         for (int ai = 0; ai < 2; ++ai)
; #pragma unroll
;             for (int m = 0; m < 4; ++m) { const int r = row0 + ai * HALF + m * 16; bf16_t* rowp = C + (size_t)r * ldc + col0; float s = 0.f;
; #pragma unroll
;                 for (int bj = 0; bj < 2; ++bj) { const f32x4 v0 = acc[ai][bj][m][0], v1 = acc[ai][bj][m][1];
;                     s += (v0[0] * v0[0] + v0[1] * v0[1]) + (v0[2] * v0[2] + v0[3] * v0[3]) + (v1[0] * v1[0] + v1[1] * v1[1]) + (v1[2] * v1[2] + v1[3] * v1[3]);
;                     u32x4 w; w.x = cvt_pk_bf16(v0[0], v0[1]); w.y = cvt_pk_bf16(v0[2], v0[3]); w.z = cvt_pk_bf16(v1[0], v1[1]); w.w = cvt_pk_bf16(v1[2], v1[3]);
;                     *(u32x4*)(rowp + bj * HALF) = w; }
;                 s += __shfl_xor(s, 16); s += __shfl_xor(s, 32);
;                 if (fq == 0) ssq[(size_t)r * 32 + u.pn * 4 + wc] = s; }
.LBB0_1426:
	s_or_b64 exec, exec, s[26:27]
	v_mul_f32_e32 v84, v77, v77
	s_waitcnt lgkmcnt(0)
	v_mul_f32_e32 v85, v79, v79
	v_fmac_f32_e32 v84, v76, v76
	v_fmac_f32_e32 v85, v78, v78
	v_cvt_pk_bf16_f32 v76, v76, v77
	v_cvt_pk_bf16_f32 v77, v78, v79
	v_mul_f32_e32 v78, v69, v69
	v_mul_f32_e32 v79, v71, v71
	v_fmac_f32_e32 v78, v68, v68
	v_fmac_f32_e32 v79, v70, v70
	v_add_f32_e32 v84, v84, v85
	v_mul_f32_e32 v85, v73, v73
	v_add_f32_e32 v78, v78, v79
	v_mul_f32_e32 v79, v65, v65
	v_fmac_f32_e32 v85, v72, v72
	v_fmac_f32_e32 v79, v64, v64
	v_add_f32_e32 v84, v84, v85
	v_mul_f32_e32 v85, v75, v75
	v_add_f32_e32 v78, v78, v79
	v_mul_f32_e32 v79, v67, v67
	v_fmac_f32_e32 v85, v74, v74
	v_fmac_f32_e32 v79, v66, v66
	v_add_f32_e32 v84, v85, v84
	v_add_f32_e32 v78, v79, v78
	v_add_f32_e32 v84, v84, v78
	v_or_b32_e32 v80, 48, v146
	ds_bpermute_b32 v85, v124, v84
	v_ashrrev_i32_e32 v81, 31, v80
	v_lshlrev_b64 v[82:83], 12, v[80:81]
	v_lshl_add_u64 v[82:83], s[14:15], 0, v[82:83]
	v_lshl_add_u64 v[82:83], v[144:145], 1, v[82:83]
	v_cvt_pk_bf16_f32 v78, v72, v73
	v_cvt_pk_bf16_f32 v79, v74, v75
	global_store_dwordx4 v[82:83], v[76:79], off sc1
	v_cvt_pk_bf16_f32 v72, v68, v69
	s_waitcnt lgkmcnt(0)
	v_add_f32_e32 v68, v84, v85
	ds_bpermute_b32 v69, v116, v68
	v_cvt_pk_bf16_f32 v73, v70, v71
	v_cvt_pk_bf16_f32 v74, v64, v65
	v_cvt_pk_bf16_f32 v75, v66, v67
	global_store_dwordx4 v[82:83], v[72:75], off offset:256 sc1
	s_and_saveexec_b64 s[26:27], s[0:1]
	s_cbranch_execz .LBB0_1428
	v_lshlrev_b64 v[64:65], 7, v[80:81]
	v_lshl_add_u64 v[64:65], s[16:17], 0, v[64:65]
	v_lshl_add_u64 v[64:65], s[24:25], 2, v[64:65]
	s_lshl_b32 s10, s40, 2
	v_lshl_add_u64 v[64:65], v[64:65], 0, s[10:11]
	s_waitcnt lgkmcnt(0)
	v_add_f32_e32 v66, v68, v69
	global_store_dword v[64:65], v66, off
.LBB0_1428:
	s_or_b64 exec, exec, s[26:27]
	v_mul_f32_e32 v68, v61, v61
	s_waitcnt lgkmcnt(0)
	v_mul_f32_e32 v69, v63, v63
	v_fmac_f32_e32 v68, v60, v60
	v_fmac_f32_e32 v69, v62, v62
	v_cvt_pk_bf16_f32 v60, v60, v61
	v_cvt_pk_bf16_f32 v61, v62, v63
	v_mul_f32_e32 v62, v53, v53
	v_mul_f32_e32 v63, v55, v55
	v_fmac_f32_e32 v62, v52, v52
	v_fmac_f32_e32 v63, v54, v54
	v_add_f32_e32 v68, v68, v69
	v_mul_f32_e32 v69, v57, v57
	v_add_f32_e32 v62, v62, v63
	v_mul_f32_e32 v63, v49, v49
	v_fmac_f32_e32 v69, v56, v56
	v_fmac_f32_e32 v63, v48, v48
	v_add_f32_e32 v68, v68, v69
	v_mul_f32_e32 v69, v59, v59
	v_add_f32_e32 v62, v62, v63
	v_mul_f32_e32 v63, v51, v51
	v_fmac_f32_e32 v69, v58, v58
	v_fmac_f32_e32 v63, v50, v50
	v_add_f32_e32 v68, v69, v68
	v_add_f32_e32 v62, v63, v62
	v_add_f32_e32 v68, v68, v62
	v_add_u32_e32 v64, 0x80, v146
	ds_bpermute_b32 v69, v124, v68
	v_ashrrev_i32_e32 v65, 31, v64
	v_lshlrev_b64 v[66:67], 12, v[64:65]
	v_lshl_add_u64 v[66:67], s[14:15], 0, v[66:67]
	v_lshl_add_u64 v[66:67], v[144:145], 1, v[66:67]
	v_cvt_pk_bf16_f32 v62, v56, v57
	v_cvt_pk_bf16_f32 v63, v58, v59
	global_store_dwordx4 v[66:67], v[60:63], off sc1
	v_cvt_pk_bf16_f32 v56, v52, v53
	s_waitcnt lgkmcnt(0)
	v_add_f32_e32 v52, v68, v69
	ds_bpermute_b32 v53, v116, v52
	v_cvt_pk_bf16_f32 v57, v54, v55
	v_cvt_pk_bf16_f32 v58, v48, v49
	v_cvt_pk_bf16_f32 v59, v50, v51
	global_store_dwordx4 v[66:67], v[56:59], off offset:256 sc1
	s_and_saveexec_b64 s[26:27], s[0:1]
	s_cbranch_execz .LBB0_1430
	v_lshlrev_b64 v[48:49], 7, v[64:65]
	v_lshl_add_u64 v[48:49], s[16:17], 0, v[48:49]
	v_lshl_add_u64 v[48:49], s[24:25], 2, v[48:49]
	s_lshl_b32 s10, s40, 2
	v_lshl_add_u64 v[48:49], v[48:49], 0, s[10:11]
	s_waitcnt lgkmcnt(0)
	v_add_f32_e32 v50, v52, v53
	global_store_dword v[48:49], v50, off
; __device__ __forceinline__ unsigned cvt_pk_bf16(float lo, float hi) { unsigned r; asm volatile("v_cvt_pk_bf16_f32 %0, %1, %2" : "=v"(r) : "v"(lo), "v"(hi)); return r; }
;     __device__ __forceinline__ void operator()(const f32x4 (&acc)[2][2][4][2], const Unit& u, int wr, int wc, int fr, int fq) const {
;     ...
;         for (int ai = 0; ai < 2; ++ai)
; #pragma unroll
;             for (int m = 0; m < 4; ++m) { const int r = row0 + ai * HALF + m * 16; bf16_t* rowp = C + (size_t)r * ldc + col0; float s = 0.f;
; #pragma unroll
;                 for (int bj = 0; bj < 2; ++bj) { const f32x4 v0 = acc[ai][bj][m][0], v1 = acc[ai][bj][m][1];
;                     s += (v0[0] * v0[0] + v0[1] * v0[1]) + (v0[2] * v0[2] + v0[3] * v0[3]) + (v1[0] * v1[0] + v1[1] * v1[1]) + (v1[2] * v1[2] + v1[3] * v1[3]);
;                     u32x4 w; w.x = cvt_pk_bf16(v0[0], v0[1]); w.y = cvt_pk_bf16(v0[2], v0[3]); w.z = cvt_pk_bf16(v1[0], v1[1]); w.w = cvt_pk_bf16(v1[2], v1[3]);
;                     *(u32x4*)(rowp + bj * HALF) = w; }
;                 s += __shfl_xor(s, 16); s += __shfl_xor(s, 32);
;                 if (fq == 0) ssq[(size_t)r * 32 + u.pn * 4 + wc] = s; }
.LBB0_1430:
	s_or_b64 exec, exec, s[26:27]
	v_mul_f32_e32 v52, v45, v45
	s_waitcnt lgkmcnt(0)
	v_mul_f32_e32 v53, v47, v47
	v_fmac_f32_e32 v52, v44, v44
	v_fmac_f32_e32 v53, v46, v46
	v_cvt_pk_bf16_f32 v44, v44, v45
	v_cvt_pk_bf16_f32 v45, v46, v47
	v_mul_f32_e32 v46, v37, v37
	v_mul_f32_e32 v47, v39, v39
	v_fmac_f32_e32 v46, v36, v36
	v_fmac_f32_e32 v47, v38, v38
	v_add_f32_e32 v52, v52, v53
	v_mul_f32_e32 v53, v41, v41
	v_add_f32_e32 v46, v46, v47
	v_mul_f32_e32 v47, v33, v33
	v_fmac_f32_e32 v53, v40, v40
	v_fmac_f32_e32 v47, v32, v32
	v_add_f32_e32 v52, v52, v53
	v_mul_f32_e32 v53, v43, v43
	v_add_f32_e32 v46, v46, v47
	v_mul_f32_e32 v47, v35, v35
	v_fmac_f32_e32 v53, v42, v42
	v_fmac_f32_e32 v47, v34, v34
	v_add_f32_e32 v52, v53, v52
	v_add_f32_e32 v46, v47, v46
	v_add_f32_e32 v52, v52, v46
	v_add_u32_e32 v48, 0x90, v146
	ds_bpermute_b32 v53, v124, v52
	v_ashrrev_i32_e32 v49, 31, v48
	v_lshlrev_b64 v[50:51], 12, v[48:49]
	v_lshl_add_u64 v[50:51], s[14:15], 0, v[50:51]
	v_lshl_add_u64 v[50:51], v[144:145], 1, v[50:51]
	v_cvt_pk_bf16_f32 v46, v40, v41
	v_cvt_pk_bf16_f32 v47, v42, v43
	global_store_dwordx4 v[50:51], v[44:47], off sc1
	v_cvt_pk_bf16_f32 v40, v36, v37
	s_waitcnt lgkmcnt(0)
	v_add_f32_e32 v36, v52, v53
	ds_bpermute_b32 v37, v116, v36
	v_cvt_pk_bf16_f32 v41, v38, v39
	v_cvt_pk_bf16_f32 v42, v32, v33
	v_cvt_pk_bf16_f32 v43, v34, v35
	global_store_dwordx4 v[50:51], v[40:43], off offset:256 sc1
	s_and_saveexec_b64 s[26:27], s[0:1]
	s_cbranch_execz .LBB0_1432
	v_lshlrev_b64 v[32:33], 7, v[48:49]
	v_lshl_add_u64 v[32:33], s[16:17], 0, v[32:33]
	v_lshl_add_u64 v[32:33], s[24:25], 2, v[32:33]
	s_lshl_b32 s10, s40, 2
	v_lshl_add_u64 v[32:33], v[32:33], 0, s[10:11]
	s_waitcnt lgkmcnt(0)
	v_add_f32_e32 v34, v36, v37
	global_store_dword v[32:33], v34, off
.LBB0_1432:
	s_or_b64 exec, exec, s[26:27]
	v_mul_f32_e32 v36, v29, v29
	s_waitcnt lgkmcnt(0)
	v_mul_f32_e32 v37, v31, v31
	v_fmac_f32_e32 v36, v28, v28
	v_fmac_f32_e32 v37, v30, v30
	v_cvt_pk_bf16_f32 v28, v28, v29
	v_cvt_pk_bf16_f32 v29, v30, v31
	v_mul_f32_e32 v30, v21, v21
	v_mul_f32_e32 v31, v23, v23
	v_fmac_f32_e32 v30, v20, v20
	v_fmac_f32_e32 v31, v22, v22
	v_add_f32_e32 v36, v36, v37
	v_mul_f32_e32 v37, v25, v25
	v_add_f32_e32 v30, v30, v31
	v_mul_f32_e32 v31, v17, v17
	v_fmac_f32_e32 v37, v24, v24
	v_fmac_f32_e32 v31, v16, v16
	v_add_f32_e32 v36, v36, v37
	v_mul_f32_e32 v37, v27, v27
	v_add_f32_e32 v30, v30, v31
	v_mul_f32_e32 v31, v19, v19
	v_fmac_f32_e32 v37, v26, v26
	v_fmac_f32_e32 v31, v18, v18
	v_add_f32_e32 v36, v37, v36
	v_add_f32_e32 v30, v31, v30
	v_add_f32_e32 v36, v36, v30
	v_add_u32_e32 v32, 0xa0, v146
	ds_bpermute_b32 v37, v124, v36
	v_ashrrev_i32_e32 v33, 31, v32
	v_lshlrev_b64 v[34:35], 12, v[32:33]
	v_lshl_add_u64 v[34:35], s[14:15], 0, v[34:35]
	v_lshl_add_u64 v[34:35], v[144:145], 1, v[34:35]
	v_cvt_pk_bf16_f32 v30, v24, v25
	v_cvt_pk_bf16_f32 v31, v26, v27
	global_store_dwordx4 v[34:35], v[28:31], off sc1
	v_cvt_pk_bf16_f32 v24, v20, v21
	s_waitcnt lgkmcnt(0)
	v_add_f32_e32 v20, v36, v37
	ds_bpermute_b32 v21, v116, v20
	v_cvt_pk_bf16_f32 v25, v22, v23
	v_cvt_pk_bf16_f32 v26, v16, v17
	v_cvt_pk_bf16_f32 v27, v18, v19
	global_store_dwordx4 v[34:35], v[24:27], off offset:256 sc1
	s_and_saveexec_b64 s[26:27], s[0:1]
	s_cbranch_execz .LBB0_1434
	v_lshlrev_b64 v[16:17], 7, v[32:33]
	v_lshl_add_u64 v[16:17], s[16:17], 0, v[16:17]
	v_lshl_add_u64 v[16:17], s[24:25], 2, v[16:17]
	s_lshl_b32 s10, s40, 2
	v_lshl_add_u64 v[16:17], v[16:17], 0, s[10:11]
	s_waitcnt lgkmcnt(0)
	v_add_f32_e32 v18, v20, v21
	global_store_dword v[16:17], v18, off
.LBB0_1434:
	s_or_b64 exec, exec, s[26:27]
	v_mul_f32_e32 v20, v13, v13
	s_waitcnt lgkmcnt(0)
	v_mul_f32_e32 v21, v15, v15
	v_fmac_f32_e32 v20, v12, v12
	v_fmac_f32_e32 v21, v14, v14
	v_cvt_pk_bf16_f32 v12, v12, v13
	v_cvt_pk_bf16_f32 v13, v14, v15
	v_mul_f32_e32 v14, v5, v5
	v_mul_f32_e32 v15, v7, v7
	v_fmac_f32_e32 v14, v4, v4
	v_fmac_f32_e32 v15, v6, v6
	v_add_f32_e32 v20, v20, v21
	v_mul_f32_e32 v21, v9, v9
	v_add_f32_e32 v14, v14, v15
	v_mul_f32_e32 v15, v1, v1
	v_fmac_f32_e32 v21, v8, v8
	v_fmac_f32_e32 v15, v0, v0
	v_add_f32_e32 v20, v20, v21
	v_mul_f32_e32 v21, v11, v11
	v_add_f32_e32 v14, v14, v15
	v_mul_f32_e32 v15, v3, v3
	v_fmac_f32_e32 v21, v10, v10
	v_fmac_f32_e32 v15, v2, v2
	v_add_f32_e32 v20, v21, v20
	v_add_f32_e32 v14, v15, v14
	v_add_f32_e32 v20, v20, v14
	v_add_u32_e32 v16, 0xb0, v146
	ds_bpermute_b32 v21, v124, v20
	v_ashrrev_i32_e32 v17, 31, v16
	v_lshlrev_b64 v[18:19], 12, v[16:17]
	v_lshl_add_u64 v[18:19], s[14:15], 0, v[18:19]
	v_lshl_add_u64 v[18:19], v[144:145], 1, v[18:19]
	v_cvt_pk_bf16_f32 v14, v8, v9
	v_cvt_pk_bf16_f32 v15, v10, v11
	global_store_dwordx4 v[18:19], v[12:15], off sc1
	v_cvt_pk_bf16_f32 v8, v4, v5
	s_waitcnt lgkmcnt(0)
	v_add_f32_e32 v4, v20, v21
	ds_bpermute_b32 v5, v116, v4
	v_cvt_pk_bf16_f32 v9, v6, v7
	v_cvt_pk_bf16_f32 v10, v0, v1
	v_cvt_pk_bf16_f32 v11, v2, v3
	global_store_dwordx4 v[18:19], v[8:11], off offset:256 sc1
	s_and_saveexec_b64 s[26:27], s[0:1]
	s_cbranch_execz .LBB0_1436
	v_lshlrev_b64 v[0:1], 7, v[16:17]
	v_lshl_add_u64 v[0:1], s[16:17], 0, v[0:1]
	v_lshl_add_u64 v[0:1], s[24:25], 2, v[0:1]
	s_lshl_b32 s10, s40, 2
	v_lshl_add_u64 v[0:1], v[0:1], 0, s[10:11]
	s_waitcnt lgkmcnt(0)
	v_add_f32_e32 v2, v4, v5
	global_store_dword v[0:1], v2, off

; __device__ __forceinline__ unsigned cvt_pk_bf16(float lo, float hi) { unsigned r; asm volatile("v_cvt_pk_bf16_f32 %0, %1, %2" : "=v"(r) : "v"(lo), "v"(hi)); return r; }
;     __device__ __forceinline__ void operator()(const f32x4 (&acc)[2][2][4][2], const Unit& u, int wr, int wc, int fr, int fq) const {
;         const int row0 = u.pm * BM + wr * 64 + fr, col0 = u.pn * BM + wc * 32 + 8 * fq;
; #pragma unroll
;         for (int ai = 0; ai < 2; ++ai)
; #pragma unroll
;             for (int m = 0; m < 4; ++m) { const int r = row0 + ai * HALF + m * 16; bf16_t* rowp = C + (size_t)r * ldc + col0; float s = 0.f;
; #pragma unroll
;                 for (int bj = 0; bj < 2; ++bj) { const f32x4 v0 = acc[ai][bj][m][0], v1 = acc[ai][bj][m][1];
;                     s += (v0[0] * v0[0] + v0[1] * v0[1]) + (v0[2] * v0[2] + v0[3] * v0[3]) + (v1[0] * v1[0] + v1[1] * v1[1]) + (v1[2] * v1[2] + v1[3] * v1[3]);
;                     u32x4 w; w.x = cvt_pk_bf16(v0[0], v0[1]); w.y = cvt_pk_bf16(v0[2], v0[3]); w.z = cvt_pk_bf16(v1[0], v1[1]); w.w = cvt_pk_bf16(v1[2], v1[3]);
;                     *(u32x4*)(rowp + bj * HALF) = w; }
;                 s += __shfl_xor(s, 16); s += __shfl_xor(s, 32);
;                 if (fq == 0) ssq[(size_t)r * 32 + u.pn * 4 + wc] = s; }
.LBB0_1978:
	v_lshl_add_u32 v146, s28, 8, v148
	v_ashrrev_i32_e32 v147, 31, v146
	v_lshl_or_b32 v144, s8, 8, v150
	v_lshlrev_b64 v[156:157], 12, v[146:147]
	v_ashrrev_i32_e32 v145, 31, v144
	v_lshl_add_u64 v[156:157], s[12:13], 0, v[156:157]
	v_lshl_add_u64 v[160:161], v[144:145], 1, v[156:157]
	v_mul_f32_e32 v155, v125, v125
	v_mul_f32_e32 v156, v127, v127
	v_fmac_f32_e32 v155, v124, v124
	v_fmac_f32_e32 v156, v126, v126
	v_add_f32_e32 v155, v155, v156
	v_mul_f32_e32 v156, v121, v121
	v_fmac_f32_e32 v156, v120, v120
	v_add_f32_e32 v155, v155, v156
	v_mul_f32_e32 v156, v123, v123
	v_fmac_f32_e32 v156, v122, v122
	v_add_f32_e32 v155, v156, v155
	v_cvt_pk_bf16_f32 v156, v124, v125
	v_mul_f32_e32 v124, v117, v117
	v_mul_f32_e32 v125, v119, v119
	v_fmac_f32_e32 v124, v116, v116
	v_fmac_f32_e32 v125, v118, v118
	v_add_f32_e32 v124, v124, v125
	v_mul_f32_e32 v125, v113, v113
	v_fmac_f32_e32 v125, v112, v112
	v_add_f32_e32 v124, v124, v125
	v_mul_f32_e32 v125, v115, v115
	v_fmac_f32_e32 v125, v114, v114
	v_cvt_pk_bf16_f32 v157, v126, v127
	v_add_f32_e32 v124, v125, v124
	v_and_b32_e32 v126, 64, v154
	v_add_f32_e32 v125, v155, v124
	v_xor_b32_e32 v124, 16, v154
	v_add_u32_e32 v126, 64, v126
	v_cmp_lt_i32_e32 vcc, v124, v126
	v_cvt_pk_bf16_f32 v158, v120, v121
	v_cvt_pk_bf16_f32 v159, v122, v123
	global_store_dwordx4 v[160:161], v[156:159], off sc1
	s_lshl_b32 s28, s8, 2
	v_cndmask_b32_e32 v124, v154, v124, vcc
	v_lshlrev_b32_e32 v124, 2, v124
	ds_bpermute_b32 v127, v124, v125
	v_cvt_pk_bf16_f32 v156, v116, v117
	v_xor_b32_e32 v116, 32, v154
	v_cmp_lt_i32_e32 vcc, v116, v126
	s_ashr_i32 s29, s28, 31
	s_waitcnt lgkmcnt(0)
	v_add_f32_e32 v117, v125, v127
	v_cndmask_b32_e32 v116, v154, v116, vcc
	v_lshlrev_b32_e32 v116, 2, v116
	ds_bpermute_b32 v120, v116, v117
	v_cvt_pk_bf16_f32 v157, v118, v119
	v_cvt_pk_bf16_f32 v158, v112, v113
	v_cvt_pk_bf16_f32 v159, v114, v115
	global_store_dwordx4 v[160:161], v[156:159], off offset:256 sc1
	s_and_saveexec_b64 s[30:31], s[0:1]
	s_cbranch_execz .LBB0_1980
	v_lshlrev_b64 v[112:113], 7, v[146:147]
	v_lshl_add_u64 v[112:113], s[14:15], 0, v[112:113]
	v_lshl_add_u64 v[112:113], s[28:29], 2, v[112:113]
	s_lshl_b32 s8, s46, 2
	v_lshl_add_u64 v[112:113], v[112:113], 0, s[8:9]
	s_waitcnt lgkmcnt(0)
	v_add_f32_e32 v114, v117, v120
	global_store_dword v[112:113], v114, off
.LBB0_1980:
	s_or_b64 exec, exec, s[30:31]
	v_mul_f32_e32 v117, v109, v109
	v_mul_f32_e32 v118, v111, v111
	v_fmac_f32_e32 v117, v108, v108
	v_fmac_f32_e32 v118, v110, v110
	v_cvt_pk_bf16_f32 v108, v108, v109
	v_cvt_pk_bf16_f32 v109, v110, v111
	v_mul_f32_e32 v110, v101, v101
	v_mul_f32_e32 v111, v103, v103
	v_fmac_f32_e32 v110, v100, v100
	v_fmac_f32_e32 v111, v102, v102
	v_add_f32_e32 v117, v117, v118
	v_mul_f32_e32 v118, v105, v105
	v_add_f32_e32 v110, v110, v111
	v_mul_f32_e32 v111, v97, v97
	v_fmac_f32_e32 v118, v104, v104
	v_fmac_f32_e32 v111, v96, v96
	v_add_f32_e32 v117, v117, v118
	v_mul_f32_e32 v118, v107, v107
	v_add_f32_e32 v110, v110, v111
	v_mul_f32_e32 v111, v99, v99
	v_fmac_f32_e32 v118, v106, v106
	v_fmac_f32_e32 v111, v98, v98
	v_add_f32_e32 v117, v118, v117
	v_add_f32_e32 v110, v111, v110
	v_add_f32_e32 v117, v117, v110
	v_or_b32_e32 v112, 16, v146
	ds_bpermute_b32 v118, v124, v117
	v_ashrrev_i32_e32 v113, 31, v112
	v_lshlrev_b64 v[114:115], 12, v[112:113]
	v_lshl_add_u64 v[114:115], s[12:13], 0, v[114:115]
	v_lshl_add_u64 v[114:115], v[144:145], 1, v[114:115]
	v_cvt_pk_bf16_f32 v110, v104, v105
	v_cvt_pk_bf16_f32 v111, v106, v107
	global_store_dwordx4 v[114:115], v[108:111], off sc1
	v_cvt_pk_bf16_f32 v104, v100, v101
	s_waitcnt lgkmcnt(0)
	v_add_f32_e32 v100, v117, v118
	ds_bpermute_b32 v101, v116, v100
	v_cvt_pk_bf16_f32 v105, v102, v103
	v_cvt_pk_bf16_f32 v106, v96, v97
	v_cvt_pk_bf16_f32 v107, v98, v99
	global_store_dwordx4 v[114:115], v[104:107], off offset:256 sc1
	s_and_saveexec_b64 s[30:31], s[0:1]
	s_cbranch_execz .LBB0_1982
	v_lshlrev_b64 v[96:97], 7, v[112:113]
	v_lshl_add_u64 v[96:97], s[14:15], 0, v[96:97]
	v_lshl_add_u64 v[96:97], s[28:29], 2, v[96:97]
	s_lshl_b32 s8, s46, 2
	v_lshl_add_u64 v[96:97], v[96:97], 0, s[8:9]
	s_waitcnt lgkmcnt(0)
	v_add_f32_e32 v98, v100, v101
	global_store_dword v[96:97], v98, off
.LBB0_1982:
	s_or_b64 exec, exec, s[30:31]
	v_mul_f32_e32 v100, v93, v93
	s_waitcnt lgkmcnt(0)
	v_mul_f32_e32 v101, v95, v95
	v_fmac_f32_e32 v100, v92, v92
	v_fmac_f32_e32 v101, v94, v94
	v_cvt_pk_bf16_f32 v92, v92, v93
	v_cvt_pk_bf16_f32 v93, v94, v95
	v_mul_f32_e32 v94, v85, v85
	v_mul_f32_e32 v95, v87, v87
	v_fmac_f32_e32 v94, v84, v84
	v_fmac_f32_e32 v95, v86, v86
	v_add_f32_e32 v100, v100, v101
	v_mul_f32_e32 v101, v89, v89
	v_add_f32_e32 v94, v94, v95
	v_mul_f32_e32 v95, v81, v81
	v_fmac_f32_e32 v101, v88, v88
	v_fmac_f32_e32 v95, v80, v80
	v_add_f32_e32 v100, v100, v101
	v_mul_f32_e32 v101, v91, v91
	v_add_f32_e32 v94, v94, v95
	v_mul_f32_e32 v95, v83, v83
	v_fmac_f32_e32 v101, v90, v90
	v_fmac_f32_e32 v95, v82, v82
	v_add_f32_e32 v100, v101, v100
	v_add_f32_e32 v94, v95, v94
	v_add_f32_e32 v100, v100, v94
	v_or_b32_e32 v96, 32, v146
	ds_bpermute_b32 v101, v124, v100
	v_ashrrev_i32_e32 v97, 31, v96
	v_lshlrev_b64 v[98:99], 12, v[96:97]
	v_lshl_add_u64 v[98:99], s[12:13], 0, v[98:99]
	v_lshl_add_u64 v[98:99], v[144:145], 1, v[98:99]
	v_cvt_pk_bf16_f32 v94, v88, v89
	v_cvt_pk_bf16_f32 v95, v90, v91
	global_store_dwordx4 v[98:99], v[92:95], off sc1
	v_cvt_pk_bf16_f32 v88, v84, v85
	s_waitcnt lgkmcnt(0)
	v_add_f32_e32 v84, v100, v101
	ds_bpermute_b32 v85, v116, v84
	v_cvt_pk_bf16_f32 v89, v86, v87
	v_cvt_pk_bf16_f32 v90, v80, v81
	v_cvt_pk_bf16_f32 v91, v82, v83
	global_store_dwordx4 v[98:99], v[88:91], off offset:256 sc1
	s_and_saveexec_b64 s[30:31], s[0:1]
	s_cbranch_execz .LBB0_1984
	v_lshlrev_b64 v[80:81], 7, v[96:97]
	v_lshl_add_u64 v[80:81], s[14:15], 0, v[80:81]
	v_lshl_add_u64 v[80:81], s[28:29], 2, v[80:81]
	s_lshl_b32 s8, s46, 2
	v_lshl_add_u64 v[80:81], v[80:81], 0, s[8:9]
	s_waitcnt lgkmcnt(0)
	v_add_f32_e32 v82, v84, v85
	global_store_dword v[80:81], v82, off
; __device__ __forceinline__ unsigned cvt_pk_bf16(float lo, float hi) { unsigned r; asm volatile("v_cvt_pk_bf16_f32 %0, %1, %2" : "=v"(r) : "v"(lo), "v"(hi)); return r; }
;     __device__ __forceinline__ void operator()(const f32x4 (&acc)[2][2][4][2], const Unit& u, int wr, int wc, int fr, int fq) const {
;     ...
;         for (int ai = 0; ai < 2; ++ai)
; #pragma unroll
;             for (int m = 0; m < 4; ++m) { const int r = row0 + ai * HALF + m * 16; bf16_t* rowp = C + (size_t)r * ldc + col0; float s = 0.f;
; #pragma unroll
;                 for (int bj = 0; bj < 2; ++bj) { const f32x4 v0 = acc[ai][bj][m][0], v1 = acc[ai][bj][m][1];
;                     s += (v0[0] * v0[0] + v0[1] * v0[1]) + (v0[2] * v0[2] + v0[3] * v0[3]) + (v1[0] * v1[0] + v1[1] * v1[1]) + (v1[2] * v1[2] + v1[3] * v1[3]);
;                     u32x4 w; w.x = cvt_pk_bf16(v0[0], v0[1]); w.y = cvt_pk_bf16(v0[2], v0[3]); w.z = cvt_pk_bf16(v1[0], v1[1]); w.w = cvt_pk_bf16(v1[2], v1[3]);
;                     *(u32x4*)(rowp + bj * HALF) = w; }
;                 s += __shfl_xor(s, 16); s += __shfl_xor(s, 32);
;                 if (fq == 0) ssq[(size_t)r * 32 + u.pn * 4 + wc] = s; }
.LBB0_1984:
	s_or_b64 exec, exec, s[30:31]
	v_mul_f32_e32 v84, v77, v77
	s_waitcnt lgkmcnt(0)
	v_mul_f32_e32 v85, v79, v79
	v_fmac_f32_e32 v84, v76, v76
	v_fmac_f32_e32 v85, v78, v78
	v_cvt_pk_bf16_f32 v76, v76, v77
	v_cvt_pk_bf16_f32 v77, v78, v79
	v_mul_f32_e32 v78, v69, v69
	v_mul_f32_e32 v79, v71, v71
	v_fmac_f32_e32 v78, v68, v68
	v_fmac_f32_e32 v79, v70, v70
	v_add_f32_e32 v84, v84, v85
	v_mul_f32_e32 v85, v73, v73
	v_add_f32_e32 v78, v78, v79
	v_mul_f32_e32 v79, v65, v65
	v_fmac_f32_e32 v85, v72, v72
	v_fmac_f32_e32 v79, v64, v64
	v_add_f32_e32 v84, v84, v85
	v_mul_f32_e32 v85, v75, v75
	v_add_f32_e32 v78, v78, v79
	v_mul_f32_e32 v79, v67, v67
	v_fmac_f32_e32 v85, v74, v74
	v_fmac_f32_e32 v79, v66, v66
	v_add_f32_e32 v84, v85, v84
	v_add_f32_e32 v78, v79, v78
	v_add_f32_e32 v84, v84, v78
	v_or_b32_e32 v80, 48, v146
	ds_bpermute_b32 v85, v124, v84
	v_ashrrev_i32_e32 v81, 31, v80
	v_lshlrev_b64 v[82:83], 12, v[80:81]
	v_lshl_add_u64 v[82:83], s[12:13], 0, v[82:83]
	v_lshl_add_u64 v[82:83], v[144:145], 1, v[82:83]
	v_cvt_pk_bf16_f32 v78, v72, v73
	v_cvt_pk_bf16_f32 v79, v74, v75
	global_store_dwordx4 v[82:83], v[76:79], off sc1
	v_cvt_pk_bf16_f32 v72, v68, v69
	s_waitcnt lgkmcnt(0)
	v_add_f32_e32 v68, v84, v85
	ds_bpermute_b32 v69, v116, v68
	v_cvt_pk_bf16_f32 v73, v70, v71
	v_cvt_pk_bf16_f32 v74, v64, v65
	v_cvt_pk_bf16_f32 v75, v66, v67
	global_store_dwordx4 v[82:83], v[72:75], off offset:256 sc1
	s_and_saveexec_b64 s[30:31], s[0:1]
	s_cbranch_execz .LBB0_1986
	v_lshlrev_b64 v[64:65], 7, v[80:81]
	v_lshl_add_u64 v[64:65], s[14:15], 0, v[64:65]
	v_lshl_add_u64 v[64:65], s[28:29], 2, v[64:65]
	s_lshl_b32 s8, s46, 2
	v_lshl_add_u64 v[64:65], v[64:65], 0, s[8:9]
	s_waitcnt lgkmcnt(0)
	v_add_f32_e32 v66, v68, v69
	global_store_dword v[64:65], v66, off
.LBB0_1986:
	s_or_b64 exec, exec, s[30:31]
	v_mul_f32_e32 v68, v61, v61
	s_waitcnt lgkmcnt(0)
	v_mul_f32_e32 v69, v63, v63
	v_fmac_f32_e32 v68, v60, v60
	v_fmac_f32_e32 v69, v62, v62
	v_cvt_pk_bf16_f32 v60, v60, v61
	v_cvt_pk_bf16_f32 v61, v62, v63
	v_mul_f32_e32 v62, v53, v53
	v_mul_f32_e32 v63, v55, v55
	v_fmac_f32_e32 v62, v52, v52
	v_fmac_f32_e32 v63, v54, v54
	v_add_f32_e32 v68, v68, v69
	v_mul_f32_e32 v69, v57, v57
	v_add_f32_e32 v62, v62, v63
	v_mul_f32_e32 v63, v49, v49
	v_fmac_f32_e32 v69, v56, v56
	v_fmac_f32_e32 v63, v48, v48
	v_add_f32_e32 v68, v68, v69
	v_mul_f32_e32 v69, v59, v59
	v_add_f32_e32 v62, v62, v63
	v_mul_f32_e32 v63, v51, v51
	v_fmac_f32_e32 v69, v58, v58
	v_fmac_f32_e32 v63, v50, v50
	v_add_f32_e32 v68, v69, v68
	v_add_f32_e32 v62, v63, v62
	v_add_f32_e32 v68, v68, v62
	v_add_u32_e32 v64, 0x80, v146
	ds_bpermute_b32 v69, v124, v68
	v_ashrrev_i32_e32 v65, 31, v64
	v_lshlrev_b64 v[66:67], 12, v[64:65]
	v_lshl_add_u64 v[66:67], s[12:13], 0, v[66:67]
	v_lshl_add_u64 v[66:67], v[144:145], 1, v[66:67]
	v_cvt_pk_bf16_f32 v62, v56, v57
	v_cvt_pk_bf16_f32 v63, v58, v59
	global_store_dwordx4 v[66:67], v[60:63], off sc1
	v_cvt_pk_bf16_f32 v56, v52, v53
	s_waitcnt lgkmcnt(0)
	v_add_f32_e32 v52, v68, v69
	ds_bpermute_b32 v53, v116, v52
	v_cvt_pk_bf16_f32 v57, v54, v55
	v_cvt_pk_bf16_f32 v58, v48, v49
	v_cvt_pk_bf16_f32 v59, v50, v51
	global_store_dwordx4 v[66:67], v[56:59], off offset:256 sc1
	s_and_saveexec_b64 s[30:31], s[0:1]
	s_cbranch_execz .LBB0_1988
	v_lshlrev_b64 v[48:49], 7, v[64:65]
	v_lshl_add_u64 v[48:49], s[14:15], 0, v[48:49]
	v_lshl_add_u64 v[48:49], s[28:29], 2, v[48:49]
	s_lshl_b32 s8, s46, 2
	v_lshl_add_u64 v[48:49], v[48:49], 0, s[8:9]
	s_waitcnt lgkmcnt(0)
	v_add_f32_e32 v50, v52, v53
	global_store_dword v[48:49], v50, off
; __device__ __forceinline__ unsigned cvt_pk_bf16(float lo, float hi) { unsigned r; asm volatile("v_cvt_pk_bf16_f32 %0, %1, %2" : "=v"(r) : "v"(lo), "v"(hi)); return r; }
;     __device__ __forceinline__ void operator()(const f32x4 (&acc)[2][2][4][2], const Unit& u, int wr, int wc, int fr, int fq) const {
;     ...
;         for (int ai = 0; ai < 2; ++ai)
; #pragma unroll
;             for (int m = 0; m < 4; ++m) { const int r = row0 + ai * HALF + m * 16; bf16_t* rowp = C + (size_t)r * ldc + col0; float s = 0.f;
; #pragma unroll
;                 for (int bj = 0; bj < 2; ++bj) { const f32x4 v0 = acc[ai][bj][m][0], v1 = acc[ai][bj][m][1];
;                     s += (v0[0] * v0[0] + v0[1] * v0[1]) + (v0[2] * v0[2] + v0[3] * v0[3]) + (v1[0] * v1[0] + v1[1] * v1[1]) + (v1[2] * v1[2] + v1[3] * v1[3]);
;                     u32x4 w; w.x = cvt_pk_bf16(v0[0], v0[1]); w.y = cvt_pk_bf16(v0[2], v0[3]); w.z = cvt_pk_bf16(v1[0], v1[1]); w.w = cvt_pk_bf16(v1[2], v1[3]);
;                     *(u32x4*)(rowp + bj * HALF) = w; }
;                 s += __shfl_xor(s, 16); s += __shfl_xor(s, 32);
;                 if (fq == 0) ssq[(size_t)r * 32 + u.pn * 4 + wc] = s; }
.LBB0_1988:
	s_or_b64 exec, exec, s[30:31]
	v_mul_f32_e32 v52, v45, v45
	s_waitcnt lgkmcnt(0)
	v_mul_f32_e32 v53, v47, v47
	v_fmac_f32_e32 v52, v44, v44
	v_fmac_f32_e32 v53, v46, v46
	v_cvt_pk_bf16_f32 v44, v44, v45
	v_cvt_pk_bf16_f32 v45, v46, v47
	v_mul_f32_e32 v46, v37, v37
	v_mul_f32_e32 v47, v39, v39
	v_fmac_f32_e32 v46, v36, v36
	v_fmac_f32_e32 v47, v38, v38
	v_add_f32_e32 v52, v52, v53
	v_mul_f32_e32 v53, v41, v41
	v_add_f32_e32 v46, v46, v47
	v_mul_f32_e32 v47, v33, v33
	v_fmac_f32_e32 v53, v40, v40
	v_fmac_f32_e32 v47, v32, v32
	v_add_f32_e32 v52, v52, v53
	v_mul_f32_e32 v53, v43, v43
	v_add_f32_e32 v46, v46, v47
	v_mul_f32_e32 v47, v35, v35
	v_fmac_f32_e32 v53, v42, v42
	v_fmac_f32_e32 v47, v34, v34
	v_add_f32_e32 v52, v53, v52
	v_add_f32_e32 v46, v47, v46
	v_add_f32_e32 v52, v52, v46
	v_add_u32_e32 v48, 0x90, v146
	ds_bpermute_b32 v53, v124, v52
	v_ashrrev_i32_e32 v49, 31, v48
	v_lshlrev_b64 v[50:51], 12, v[48:49]
	v_lshl_add_u64 v[50:51], s[12:13], 0, v[50:51]
	v_lshl_add_u64 v[50:51], v[144:145], 1, v[50:51]
	v_cvt_pk_bf16_f32 v46, v40, v41
	v_cvt_pk_bf16_f32 v47, v42, v43
	global_store_dwordx4 v[50:51], v[44:47], off sc1
	v_cvt_pk_bf16_f32 v40, v36, v37
	s_waitcnt lgkmcnt(0)
	v_add_f32_e32 v36, v52, v53
	ds_bpermute_b32 v37, v116, v36
	v_cvt_pk_bf16_f32 v41, v38, v39
	v_cvt_pk_bf16_f32 v42, v32, v33
	v_cvt_pk_bf16_f32 v43, v34, v35
	global_store_dwordx4 v[50:51], v[40:43], off offset:256 sc1
	s_and_saveexec_b64 s[30:31], s[0:1]
	s_cbranch_execz .LBB0_1990
	v_lshlrev_b64 v[32:33], 7, v[48:49]
	v_lshl_add_u64 v[32:33], s[14:15], 0, v[32:33]
	v_lshl_add_u64 v[32:33], s[28:29], 2, v[32:33]
	s_lshl_b32 s8, s46, 2
	v_lshl_add_u64 v[32:33], v[32:33], 0, s[8:9]
	s_waitcnt lgkmcnt(0)
	v_add_f32_e32 v34, v36, v37
	global_store_dword v[32:33], v34, off
.LBB0_1990:
	s_or_b64 exec, exec, s[30:31]
	v_mul_f32_e32 v36, v29, v29
	s_waitcnt lgkmcnt(0)
	v_mul_f32_e32 v37, v31, v31
	v_fmac_f32_e32 v36, v28, v28
	v_fmac_f32_e32 v37, v30, v30
	v_cvt_pk_bf16_f32 v28, v28, v29
	v_cvt_pk_bf16_f32 v29, v30, v31
	v_mul_f32_e32 v30, v21, v21
	v_mul_f32_e32 v31, v23, v23
	v_fmac_f32_e32 v30, v20, v20
	v_fmac_f32_e32 v31, v22, v22
	v_add_f32_e32 v36, v36, v37
	v_mul_f32_e32 v37, v25, v25
	v_add_f32_e32 v30, v30, v31
	v_mul_f32_e32 v31, v17, v17
	v_fmac_f32_e32 v37, v24, v24
	v_fmac_f32_e32 v31, v16, v16
	v_add_f32_e32 v36, v36, v37
	v_mul_f32_e32 v37, v27, v27
	v_add_f32_e32 v30, v30, v31
	v_mul_f32_e32 v31, v19, v19
	v_fmac_f32_e32 v37, v26, v26
	v_fmac_f32_e32 v31, v18, v18
	v_add_f32_e32 v36, v37, v36
	v_add_f32_e32 v30, v31, v30
	v_add_f32_e32 v36, v36, v30
	v_add_u32_e32 v32, 0xa0, v146
	ds_bpermute_b32 v37, v124, v36
	v_ashrrev_i32_e32 v33, 31, v32
	v_lshlrev_b64 v[34:35], 12, v[32:33]
	v_lshl_add_u64 v[34:35], s[12:13], 0, v[34:35]
	v_lshl_add_u64 v[34:35], v[144:145], 1, v[34:35]
	v_cvt_pk_bf16_f32 v30, v24, v25
	v_cvt_pk_bf16_f32 v31, v26, v27
	global_store_dwordx4 v[34:35], v[28:31], off sc1
	v_cvt_pk_bf16_f32 v24, v20, v21
	s_waitcnt lgkmcnt(0)
	v_add_f32_e32 v20, v36, v37
	ds_bpermute_b32 v21, v116, v20
	v_cvt_pk_bf16_f32 v25, v22, v23
	v_cvt_pk_bf16_f32 v26, v16, v17
	v_cvt_pk_bf16_f32 v27, v18, v19
	global_store_dwordx4 v[34:35], v[24:27], off offset:256 sc1
	s_and_saveexec_b64 s[30:31], s[0:1]
	s_cbranch_execz .LBB0_1992
	v_lshlrev_b64 v[16:17], 7, v[32:33]
	v_lshl_add_u64 v[16:17], s[14:15], 0, v[16:17]
	v_lshl_add_u64 v[16:17], s[28:29], 2, v[16:17]
	s_lshl_b32 s8, s46, 2
	v_lshl_add_u64 v[16:17], v[16:17], 0, s[8:9]
	s_waitcnt lgkmcnt(0)
	v_add_f32_e32 v18, v20, v21
	global_store_dword v[16:17], v18, off
.LBB0_1992:
	s_or_b64 exec, exec, s[30:31]
	v_mul_f32_e32 v20, v13, v13
	s_waitcnt lgkmcnt(0)
	v_mul_f32_e32 v21, v15, v15
	v_fmac_f32_e32 v20, v12, v12
	v_fmac_f32_e32 v21, v14, v14
	v_cvt_pk_bf16_f32 v12, v12, v13
	v_cvt_pk_bf16_f32 v13, v14, v15
	v_mul_f32_e32 v14, v5, v5
	v_mul_f32_e32 v15, v7, v7
	v_fmac_f32_e32 v14, v4, v4
	v_fmac_f32_e32 v15, v6, v6
	v_add_f32_e32 v20, v20, v21
	v_mul_f32_e32 v21, v9, v9
	v_add_f32_e32 v14, v14, v15
	v_mul_f32_e32 v15, v1, v1
	v_fmac_f32_e32 v21, v8, v8
	v_fmac_f32_e32 v15, v0, v0
	v_add_f32_e32 v20, v20, v21
	v_mul_f32_e32 v21, v11, v11
	v_add_f32_e32 v14, v14, v15
	v_mul_f32_e32 v15, v3, v3
	v_fmac_f32_e32 v21, v10, v10
	v_fmac_f32_e32 v15, v2, v2
	v_add_f32_e32 v20, v21, v20
	v_add_f32_e32 v14, v15, v14
	v_add_f32_e32 v20, v20, v14
	v_add_u32_e32 v16, 0xb0, v146
	ds_bpermute_b32 v21, v124, v20
	v_ashrrev_i32_e32 v17, 31, v16
	v_lshlrev_b64 v[18:19], 12, v[16:17]
	v_lshl_add_u64 v[18:19], s[12:13], 0, v[18:19]
	v_lshl_add_u64 v[18:19], v[144:145], 1, v[18:19]
	v_cvt_pk_bf16_f32 v14, v8, v9
	v_cvt_pk_bf16_f32 v15, v10, v11
	global_store_dwordx4 v[18:19], v[12:15], off sc1
	v_cvt_pk_bf16_f32 v8, v4, v5
	s_waitcnt lgkmcnt(0)
	v_add_f32_e32 v4, v20, v21
	ds_bpermute_b32 v5, v116, v4
	v_cvt_pk_bf16_f32 v9, v6, v7
	v_cvt_pk_bf16_f32 v10, v0, v1
	v_cvt_pk_bf16_f32 v11, v2, v3
	global_store_dwordx4 v[18:19], v[8:11], off offset:256 sc1
	s_and_saveexec_b64 s[30:31], s[0:1]
	s_cbranch_execz .LBB0_1994
	v_lshlrev_b64 v[0:1], 7, v[16:17]
	v_lshl_add_u64 v[0:1], s[14:15], 0, v[0:1]
	v_lshl_add_u64 v[0:1], s[28:29], 2, v[0:1]
	s_lshl_b32 s8, s46, 2
	v_lshl_add_u64 v[0:1], v[0:1], 0, s[8:9]
	s_waitcnt lgkmcnt(0)
	v_add_f32_e32 v2, v4, v5
	global_store_dword v[0:1], v2, off

; __device__ __forceinline__ unsigned cvt_pk_bf16(float lo, float hi) { unsigned r; asm volatile("v_cvt_pk_bf16_f32 %0, %1, %2" : "=v"(r) : "v"(lo), "v"(hi)); return r; }
;     __device__ __forceinline__ void operator()(const f32x4 (&acc)[2][2][4][2], const Unit& u, int wr, int wc, int fr, int fq) const {
;         const int row0 = u.pm * BM + wr * 64 + fr, col0 = u.pn * BM + wc * 32 + 8 * fq;
; #pragma unroll
;         for (int ai = 0; ai < 2; ++ai)
; #pragma unroll
;             for (int m = 0; m < 4; ++m) { const int r = row0 + ai * HALF + m * 16; bf16_t* rowp = C + (size_t)r * ldc + col0; float s = 0.f;
; #pragma unroll
;                 for (int bj = 0; bj < 2; ++bj) { const f32x4 v0 = acc[ai][bj][m][0], v1 = acc[ai][bj][m][1];
;                     s += (v0[0] * v0[0] + v0[1] * v0[1]) + (v0[2] * v0[2] + v0[3] * v0[3]) + (v1[0] * v1[0] + v1[1] * v1[1]) + (v1[2] * v1[2] + v1[3] * v1[3]);
;                     u32x4 w; w.x = cvt_pk_bf16(v0[0], v0[1]); w.y = cvt_pk_bf16(v0[2], v0[3]); w.z = cvt_pk_bf16(v1[0], v1[1]); w.w = cvt_pk_bf16(v1[2], v1[3]);
;                     *(u32x4*)(rowp + bj * HALF) = w; }
.LBB0_2200:
	v_lshl_add_u32 v146, s50, 8, v148
	v_ashrrev_i32_e32 v147, 31, v146
	v_lshl_or_b32 v144, s10, 8, v150
	v_lshlrev_b64 v[156:157], 12, v[146:147]
	v_ashrrev_i32_e32 v145, 31, v144
	v_lshl_add_u64 v[156:157], s[14:15], 0, v[156:157]
	v_lshl_add_u64 v[160:161], v[144:145], 1, v[156:157]
	v_mul_f32_e32 v155, v125, v125
	v_mul_f32_e32 v156, v127, v127
	v_fmac_f32_e32 v155, v124, v124
	v_fmac_f32_e32 v156, v126, v126
	v_add_f32_e32 v155, v155, v156
	v_mul_f32_e32 v156, v121, v121
	v_fmac_f32_e32 v156, v120, v120
	v_add_f32_e32 v155, v155, v156
	v_mul_f32_e32 v156, v123, v123
	v_fmac_f32_e32 v156, v122, v122
	v_add_f32_e32 v155, v156, v155
	v_cvt_pk_bf16_f32 v156, v124, v125
	v_mul_f32_e32 v124, v117, v117
	v_mul_f32_e32 v125, v119, v119
	v_fmac_f32_e32 v124, v116, v116
	v_fmac_f32_e32 v125, v118, v118
	v_add_f32_e32 v124, v124, v125
	v_mul_f32_e32 v125, v113, v113
	v_fmac_f32_e32 v125, v112, v112
	v_add_f32_e32 v124, v124, v125
	v_mul_f32_e32 v125, v115, v115
	v_fmac_f32_e32 v125, v114, v114
	v_cvt_pk_bf16_f32 v157, v126, v127
	v_add_f32_e32 v124, v125, v124
	v_and_b32_e32 v126, 64, v154
	v_add_f32_e32 v125, v155, v124
	v_xor_b32_e32 v124, 16, v154
	v_add_u32_e32 v126, 64, v126
	v_cmp_lt_i32_e32 vcc, v124, v126
	v_cvt_pk_bf16_f32 v158, v120, v121
	v_cvt_pk_bf16_f32 v159, v122, v123
	global_store_dwordx4 v[160:161], v[156:159], off sc1
	s_lshl_b32 s24, s10, 2
	v_cndmask_b32_e32 v124, v154, v124, vcc
	v_lshlrev_b32_e32 v124, 2, v124
	ds_bpermute_b32 v127, v124, v125
	v_cvt_pk_bf16_f32 v156, v116, v117
	v_xor_b32_e32 v116, 32, v154
	v_cmp_lt_i32_e32 vcc, v116, v126
	s_ashr_i32 s25, s24, 31
	s_waitcnt lgkmcnt(0)
	v_add_f32_e32 v117, v125, v127
	v_cndmask_b32_e32 v116, v154, v116, vcc
	v_lshlrev_b32_e32 v116, 2, v116
	ds_bpermute_b32 v120, v116, v117
	v_cvt_pk_bf16_f32 v157, v118, v119
	v_cvt_pk_bf16_f32 v158, v112, v113
	v_cvt_pk_bf16_f32 v159, v114, v115
	global_store_dwordx4 v[160:161], v[156:159], off offset:256 sc1
	s_and_saveexec_b64 s[26:27], s[0:1]
	s_cbranch_execz .LBB0_2202
	v_lshlrev_b64 v[112:113], 7, v[146:147]
	v_lshl_add_u64 v[112:113], s[16:17], 0, v[112:113]
	v_lshl_add_u64 v[112:113], s[24:25], 2, v[112:113]
	s_lshl_b32 s10, s40, 2
	v_lshl_add_u64 v[112:113], v[112:113], 0, s[10:11]
	s_waitcnt lgkmcnt(0)
	v_add_f32_e32 v114, v117, v120
	global_store_dword v[112:113], v114, off
